# ssq phase: 4 rows per wave in flight with DPP wave reduction
# baseline (speedup 1.0000x reference)
.LBB0_2166:
	s_or_b64 exec, exec, s[0:1]
	s_mov_b64 s[4:5], s[60:61]
	v_mov_b32_e32 v1, v218
	s_waitcnt lgkmcnt(0)
	v_mov_b32_e32 v0, v219
	s_barrier
	s_movk_i32 s1, 0x4000
	v_readfirstlane_b32 s0, v0
	v_mov_b32_e32 v0, v218
	s_lshl_b32 s0, s0, 2
	v_ashrrev_i32_e32 v0, 6, v0
	v_add_u32_e32 v4, s0, v0
	v_cmp_gt_i32_e32 vcc, s1, v4
	s_and_saveexec_b64 s[2:3], vcc
	s_cbranch_execz .LBB0_2171
	s_load_dwordx2 s[4:5], s[60:61], 0xe8
	v_readfirstlane_b32 s6, v4
	v_readlane_b32 s7, v252, 22
	v_lshlrev_b32_e32 v40, 4, v221
	s_waitcnt lgkmcnt(0)
.Lssq_loop:
	s_mov_b32 s100, s6
	s_min_u32 s101, s100, 0x3fff
	s_lshl_b32 s0, s101, 12
	s_add_u32 s0, s4, s0
	s_addc_u32 s1, s5, 0
	s_add_u32 s0, s0, 0x5210000
	s_addc_u32 s1, s1, 0
	global_load_dwordx4 v[44:47], v40, s[0:1]
	global_load_dwordx4 v[48:51], v40, s[0:1] offset:1024
	global_load_dwordx4 v[52:55], v40, s[0:1] offset:2048
	global_load_dwordx4 v[56:59], v40, s[0:1] offset:3072
	s_add_u32 s100, s100, s7
	s_min_u32 s101, s100, 0x3fff
	s_lshl_b32 s0, s101, 12
	s_add_u32 s0, s4, s0
	s_addc_u32 s1, s5, 0
	s_add_u32 s0, s0, 0x5210000
	s_addc_u32 s1, s1, 0
	global_load_dwordx4 v[60:63], v40, s[0:1]
	global_load_dwordx4 v[64:67], v40, s[0:1] offset:1024
	global_load_dwordx4 v[68:71], v40, s[0:1] offset:2048
	global_load_dwordx4 v[72:75], v40, s[0:1] offset:3072
	s_add_u32 s100, s100, s7
	s_min_u32 s101, s100, 0x3fff
	s_lshl_b32 s0, s101, 12
	s_add_u32 s0, s4, s0
	s_addc_u32 s1, s5, 0
	s_add_u32 s0, s0, 0x5210000
	s_addc_u32 s1, s1, 0
	global_load_dwordx4 v[76:79], v40, s[0:1]
	global_load_dwordx4 v[80:83], v40, s[0:1] offset:1024
	global_load_dwordx4 v[84:87], v40, s[0:1] offset:2048
	global_load_dwordx4 v[88:91], v40, s[0:1] offset:3072
	s_add_u32 s100, s100, s7
	s_min_u32 s101, s100, 0x3fff
	s_lshl_b32 s0, s101, 12
	s_add_u32 s0, s4, s0
	s_addc_u32 s1, s5, 0
	s_add_u32 s0, s0, 0x5210000
	s_addc_u32 s1, s1, 0
	global_load_dwordx4 v[92:95], v40, s[0:1]
	global_load_dwordx4 v[96:99], v40, s[0:1] offset:1024
	global_load_dwordx4 v[100:103], v40, s[0:1] offset:2048
	global_load_dwordx4 v[104:107], v40, s[0:1] offset:3072
	s_add_u32 s100, s100, s7
	s_waitcnt vmcnt(12)
	v_and_b32_e32 v12, 0xffff0000, v44
	v_lshlrev_b32_e32 v13, 16, v44
	v_mul_f32_e32 v108, v12, v12
	v_fmac_f32_e32 v108, v13, v13
	v_and_b32_e32 v12, 0xffff0000, v45
	v_lshlrev_b32_e32 v13, 16, v45
	v_fmac_f32_e32 v108, v12, v12
	v_fmac_f32_e32 v108, v13, v13
	v_and_b32_e32 v12, 0xffff0000, v46
	v_lshlrev_b32_e32 v13, 16, v46
	v_fmac_f32_e32 v108, v12, v12
	v_fmac_f32_e32 v108, v13, v13
	v_and_b32_e32 v12, 0xffff0000, v47
	v_lshlrev_b32_e32 v13, 16, v47
	v_fmac_f32_e32 v108, v12, v12
	v_fmac_f32_e32 v108, v13, v13
	v_and_b32_e32 v12, 0xffff0000, v48
	v_lshlrev_b32_e32 v13, 16, v48
	v_fmac_f32_e32 v108, v12, v12
	v_fmac_f32_e32 v108, v13, v13
	v_and_b32_e32 v12, 0xffff0000, v49
	v_lshlrev_b32_e32 v13, 16, v49
	v_fmac_f32_e32 v108, v12, v12
	v_fmac_f32_e32 v108, v13, v13
	v_and_b32_e32 v12, 0xffff0000, v50
	v_lshlrev_b32_e32 v13, 16, v50
	v_fmac_f32_e32 v108, v12, v12
	v_fmac_f32_e32 v108, v13, v13
	v_and_b32_e32 v12, 0xffff0000, v51
	v_lshlrev_b32_e32 v13, 16, v51
	v_fmac_f32_e32 v108, v12, v12
	v_fmac_f32_e32 v108, v13, v13
	v_and_b32_e32 v12, 0xffff0000, v52
	v_lshlrev_b32_e32 v13, 16, v52
	v_fmac_f32_e32 v108, v12, v12
	v_fmac_f32_e32 v108, v13, v13
	v_and_b32_e32 v12, 0xffff0000, v53
	v_lshlrev_b32_e32 v13, 16, v53
	v_fmac_f32_e32 v108, v12, v12
	v_fmac_f32_e32 v108, v13, v13
	v_and_b32_e32 v12, 0xffff0000, v54
	v_lshlrev_b32_e32 v13, 16, v54
	v_fmac_f32_e32 v108, v12, v12
	v_fmac_f32_e32 v108, v13, v13
	v_and_b32_e32 v12, 0xffff0000, v55
	v_lshlrev_b32_e32 v13, 16, v55
	v_fmac_f32_e32 v108, v12, v12
	v_fmac_f32_e32 v108, v13, v13
	v_and_b32_e32 v12, 0xffff0000, v56
	v_lshlrev_b32_e32 v13, 16, v56
	v_fmac_f32_e32 v108, v12, v12
	v_fmac_f32_e32 v108, v13, v13
	v_and_b32_e32 v12, 0xffff0000, v57
	v_lshlrev_b32_e32 v13, 16, v57
	v_fmac_f32_e32 v108, v12, v12
	v_fmac_f32_e32 v108, v13, v13
	v_and_b32_e32 v12, 0xffff0000, v58
	v_lshlrev_b32_e32 v13, 16, v58
	v_fmac_f32_e32 v108, v12, v12
	v_fmac_f32_e32 v108, v13, v13
	v_and_b32_e32 v12, 0xffff0000, v59
	v_lshlrev_b32_e32 v13, 16, v59
	v_fmac_f32_e32 v108, v12, v12
	v_fmac_f32_e32 v108, v13, v13
	s_waitcnt vmcnt(8)
	v_and_b32_e32 v12, 0xffff0000, v60
	v_lshlrev_b32_e32 v13, 16, v60
	v_mul_f32_e32 v109, v12, v12
	v_fmac_f32_e32 v109, v13, v13
	v_and_b32_e32 v12, 0xffff0000, v61
	v_lshlrev_b32_e32 v13, 16, v61
	v_fmac_f32_e32 v109, v12, v12
	v_fmac_f32_e32 v109, v13, v13
	v_and_b32_e32 v12, 0xffff0000, v62
	v_lshlrev_b32_e32 v13, 16, v62
	v_fmac_f32_e32 v109, v12, v12
	v_fmac_f32_e32 v109, v13, v13
	v_and_b32_e32 v12, 0xffff0000, v63
	v_lshlrev_b32_e32 v13, 16, v63
	v_fmac_f32_e32 v109, v12, v12
	v_fmac_f32_e32 v109, v13, v13
	v_and_b32_e32 v12, 0xffff0000, v64
	v_lshlrev_b32_e32 v13, 16, v64
	v_fmac_f32_e32 v109, v12, v12
	v_fmac_f32_e32 v109, v13, v13
	v_and_b32_e32 v12, 0xffff0000, v65
	v_lshlrev_b32_e32 v13, 16, v65
	v_fmac_f32_e32 v109, v12, v12
	v_fmac_f32_e32 v109, v13, v13
	v_and_b32_e32 v12, 0xffff0000, v66
	v_lshlrev_b32_e32 v13, 16, v66
	v_fmac_f32_e32 v109, v12, v12
	v_fmac_f32_e32 v109, v13, v13
	v_and_b32_e32 v12, 0xffff0000, v67
	v_lshlrev_b32_e32 v13, 16, v67
	v_fmac_f32_e32 v109, v12, v12
	v_fmac_f32_e32 v109, v13, v13
	v_and_b32_e32 v12, 0xffff0000, v68
	v_lshlrev_b32_e32 v13, 16, v68
	v_fmac_f32_e32 v109, v12, v12
	v_fmac_f32_e32 v109, v13, v13
	v_and_b32_e32 v12, 0xffff0000, v69
	v_lshlrev_b32_e32 v13, 16, v69
	v_fmac_f32_e32 v109, v12, v12
	v_fmac_f32_e32 v109, v13, v13
	v_and_b32_e32 v12, 0xffff0000, v70
	v_lshlrev_b32_e32 v13, 16, v70
	v_fmac_f32_e32 v109, v12, v12
	v_fmac_f32_e32 v109, v13, v13
	v_and_b32_e32 v12, 0xffff0000, v71
	v_lshlrev_b32_e32 v13, 16, v71
	v_fmac_f32_e32 v109, v12, v12
	v_fmac_f32_e32 v109, v13, v13
	v_and_b32_e32 v12, 0xffff0000, v72
	v_lshlrev_b32_e32 v13, 16, v72
	v_fmac_f32_e32 v109, v12, v12
	v_fmac_f32_e32 v109, v13, v13
	v_and_b32_e32 v12, 0xffff0000, v73
	v_lshlrev_b32_e32 v13, 16, v73
	v_fmac_f32_e32 v109, v12, v12
	v_fmac_f32_e32 v109, v13, v13
	v_and_b32_e32 v12, 0xffff0000, v74
	v_lshlrev_b32_e32 v13, 16, v74
	v_fmac_f32_e32 v109, v12, v12
	v_fmac_f32_e32 v109, v13, v13
	v_and_b32_e32 v12, 0xffff0000, v75
	v_lshlrev_b32_e32 v13, 16, v75
	v_fmac_f32_e32 v109, v12, v12
	v_fmac_f32_e32 v109, v13, v13
	s_waitcnt vmcnt(4)
	v_and_b32_e32 v12, 0xffff0000, v76
	v_lshlrev_b32_e32 v13, 16, v76
	v_mul_f32_e32 v110, v12, v12
	v_fmac_f32_e32 v110, v13, v13
	v_and_b32_e32 v12, 0xffff0000, v77
	v_lshlrev_b32_e32 v13, 16, v77
	v_fmac_f32_e32 v110, v12, v12
	v_fmac_f32_e32 v110, v13, v13
	v_and_b32_e32 v12, 0xffff0000, v78
	v_lshlrev_b32_e32 v13, 16, v78
	v_fmac_f32_e32 v110, v12, v12
	v_fmac_f32_e32 v110, v13, v13
	v_and_b32_e32 v12, 0xffff0000, v79
	v_lshlrev_b32_e32 v13, 16, v79
	v_fmac_f32_e32 v110, v12, v12
	v_fmac_f32_e32 v110, v13, v13
	v_and_b32_e32 v12, 0xffff0000, v80
	v_lshlrev_b32_e32 v13, 16, v80
	v_fmac_f32_e32 v110, v12, v12
	v_fmac_f32_e32 v110, v13, v13
	v_and_b32_e32 v12, 0xffff0000, v81
	v_lshlrev_b32_e32 v13, 16, v81
	v_fmac_f32_e32 v110, v12, v12
	v_fmac_f32_e32 v110, v13, v13
	v_and_b32_e32 v12, 0xffff0000, v82
	v_lshlrev_b32_e32 v13, 16, v82
	v_fmac_f32_e32 v110, v12, v12
	v_fmac_f32_e32 v110, v13, v13
	v_and_b32_e32 v12, 0xffff0000, v83
	v_lshlrev_b32_e32 v13, 16, v83
	v_fmac_f32_e32 v110, v12, v12
	v_fmac_f32_e32 v110, v13, v13
	v_and_b32_e32 v12, 0xffff0000, v84
	v_lshlrev_b32_e32 v13, 16, v84
	v_fmac_f32_e32 v110, v12, v12
	v_fmac_f32_e32 v110, v13, v13
	v_and_b32_e32 v12, 0xffff0000, v85
	v_lshlrev_b32_e32 v13, 16, v85
	v_fmac_f32_e32 v110, v12, v12
	v_fmac_f32_e32 v110, v13, v13
	v_and_b32_e32 v12, 0xffff0000, v86
	v_lshlrev_b32_e32 v13, 16, v86
	v_fmac_f32_e32 v110, v12, v12
	v_fmac_f32_e32 v110, v13, v13
	v_and_b32_e32 v12, 0xffff0000, v87
	v_lshlrev_b32_e32 v13, 16, v87
	v_fmac_f32_e32 v110, v12, v12
	v_fmac_f32_e32 v110, v13, v13
	v_and_b32_e32 v12, 0xffff0000, v88
	v_lshlrev_b32_e32 v13, 16, v88
	v_fmac_f32_e32 v110, v12, v12
	v_fmac_f32_e32 v110, v13, v13
	v_and_b32_e32 v12, 0xffff0000, v89
	v_lshlrev_b32_e32 v13, 16, v89
	v_fmac_f32_e32 v110, v12, v12
	v_fmac_f32_e32 v110, v13, v13
	v_and_b32_e32 v12, 0xffff0000, v90
	v_lshlrev_b32_e32 v13, 16, v90
	v_fmac_f32_e32 v110, v12, v12
	v_fmac_f32_e32 v110, v13, v13
	v_and_b32_e32 v12, 0xffff0000, v91
	v_lshlrev_b32_e32 v13, 16, v91
	v_fmac_f32_e32 v110, v12, v12
	v_fmac_f32_e32 v110, v13, v13
	s_waitcnt vmcnt(0)
	v_and_b32_e32 v12, 0xffff0000, v92
	v_lshlrev_b32_e32 v13, 16, v92
	v_mul_f32_e32 v111, v12, v12
	v_fmac_f32_e32 v111, v13, v13
	v_and_b32_e32 v12, 0xffff0000, v93
	v_lshlrev_b32_e32 v13, 16, v93
	v_fmac_f32_e32 v111, v12, v12
	v_fmac_f32_e32 v111, v13, v13
	v_and_b32_e32 v12, 0xffff0000, v94
	v_lshlrev_b32_e32 v13, 16, v94
	v_fmac_f32_e32 v111, v12, v12
	v_fmac_f32_e32 v111, v13, v13
	v_and_b32_e32 v12, 0xffff0000, v95
	v_lshlrev_b32_e32 v13, 16, v95
	v_fmac_f32_e32 v111, v12, v12
	v_fmac_f32_e32 v111, v13, v13
	v_and_b32_e32 v12, 0xffff0000, v96
	v_lshlrev_b32_e32 v13, 16, v96
	v_fmac_f32_e32 v111, v12, v12
	v_fmac_f32_e32 v111, v13, v13
	v_and_b32_e32 v12, 0xffff0000, v97
	v_lshlrev_b32_e32 v13, 16, v97
	v_fmac_f32_e32 v111, v12, v12
	v_fmac_f32_e32 v111, v13, v13
	v_and_b32_e32 v12, 0xffff0000, v98
	v_lshlrev_b32_e32 v13, 16, v98
	v_fmac_f32_e32 v111, v12, v12
	v_fmac_f32_e32 v111, v13, v13
	v_and_b32_e32 v12, 0xffff0000, v99
	v_lshlrev_b32_e32 v13, 16, v99
	v_fmac_f32_e32 v111, v12, v12
	v_fmac_f32_e32 v111, v13, v13
	v_and_b32_e32 v12, 0xffff0000, v100
	v_lshlrev_b32_e32 v13, 16, v100
	v_fmac_f32_e32 v111, v12, v12
	v_fmac_f32_e32 v111, v13, v13
	v_and_b32_e32 v12, 0xffff0000, v101
	v_lshlrev_b32_e32 v13, 16, v101
	v_fmac_f32_e32 v111, v12, v12
	v_fmac_f32_e32 v111, v13, v13
	v_and_b32_e32 v12, 0xffff0000, v102
	v_lshlrev_b32_e32 v13, 16, v102
	v_fmac_f32_e32 v111, v12, v12
	v_fmac_f32_e32 v111, v13, v13
	v_and_b32_e32 v12, 0xffff0000, v103
	v_lshlrev_b32_e32 v13, 16, v103
	v_fmac_f32_e32 v111, v12, v12
	v_fmac_f32_e32 v111, v13, v13
	v_and_b32_e32 v12, 0xffff0000, v104
	v_lshlrev_b32_e32 v13, 16, v104
	v_fmac_f32_e32 v111, v12, v12
	v_fmac_f32_e32 v111, v13, v13
	v_and_b32_e32 v12, 0xffff0000, v105
	v_lshlrev_b32_e32 v13, 16, v105
	v_fmac_f32_e32 v111, v12, v12
	v_fmac_f32_e32 v111, v13, v13
	v_and_b32_e32 v12, 0xffff0000, v106
	v_lshlrev_b32_e32 v13, 16, v106
	v_fmac_f32_e32 v111, v12, v12
	v_fmac_f32_e32 v111, v13, v13
	v_and_b32_e32 v12, 0xffff0000, v107
	v_lshlrev_b32_e32 v13, 16, v107
	v_fmac_f32_e32 v111, v12, v12
	v_fmac_f32_e32 v111, v13, v13
	v_add_f32_dpp v108, v108, v108 row_shr:1 row_mask:0xf bank_mask:0xf
	v_add_f32_dpp v109, v109, v109 row_shr:1 row_mask:0xf bank_mask:0xf
	v_add_f32_dpp v110, v110, v110 row_shr:1 row_mask:0xf bank_mask:0xf
	v_add_f32_dpp v111, v111, v111 row_shr:1 row_mask:0xf bank_mask:0xf
	v_add_f32_dpp v108, v108, v108 row_shr:2 row_mask:0xf bank_mask:0xf
	v_add_f32_dpp v109, v109, v109 row_shr:2 row_mask:0xf bank_mask:0xf
	v_add_f32_dpp v110, v110, v110 row_shr:2 row_mask:0xf bank_mask:0xf
	v_add_f32_dpp v111, v111, v111 row_shr:2 row_mask:0xf bank_mask:0xf
	v_add_f32_dpp v108, v108, v108 row_shr:4 row_mask:0xf bank_mask:0xf
	v_add_f32_dpp v109, v109, v109 row_shr:4 row_mask:0xf bank_mask:0xf
	v_add_f32_dpp v110, v110, v110 row_shr:4 row_mask:0xf bank_mask:0xf
	v_add_f32_dpp v111, v111, v111 row_shr:4 row_mask:0xf bank_mask:0xf
	v_add_f32_dpp v108, v108, v108 row_shr:8 row_mask:0xf bank_mask:0xf
	v_add_f32_dpp v109, v109, v109 row_shr:8 row_mask:0xf bank_mask:0xf
	v_add_f32_dpp v110, v110, v110 row_shr:8 row_mask:0xf bank_mask:0xf
	v_add_f32_dpp v111, v111, v111 row_shr:8 row_mask:0xf bank_mask:0xf
	v_add_f32_dpp v108, v108, v108 row_bcast:15 row_mask:0xa bank_mask:0xf
	v_add_f32_dpp v109, v109, v109 row_bcast:15 row_mask:0xa bank_mask:0xf
	v_add_f32_dpp v110, v110, v110 row_bcast:15 row_mask:0xa bank_mask:0xf
	v_add_f32_dpp v111, v111, v111 row_bcast:15 row_mask:0xa bank_mask:0xf
	v_add_f32_dpp v108, v108, v108 row_bcast:31 row_mask:0xc bank_mask:0xf
	v_add_f32_dpp v109, v109, v109 row_bcast:31 row_mask:0xc bank_mask:0xf
	v_add_f32_dpp v110, v110, v110 row_bcast:31 row_mask:0xc bank_mask:0xf
	v_add_f32_dpp v111, v111, v111 row_bcast:31 row_mask:0xc bank_mask:0xf
	s_nop 1
	v_readlane_b32 s0, v108, 63
	v_readlane_b32 s1, v109, 63
	v_readlane_b32 s100, v110, 63
	v_readlane_b32 s101, v111, 63
	v_mov_b32_e32 v112, s0
	v_mov_b32_e32 v113, s1
	v_mov_b32_e32 v114, s100
	v_mov_b32_e32 v115, s101
	v_fmamk_f32 v112, v112, 0x3a000000, v162
	v_fmamk_f32 v113, v113, 0x3a000000, v162
	v_fmamk_f32 v114, v114, 0x3a000000, v162
	v_fmamk_f32 v115, v115, 0x3a000000, v162
	v_mul_f32_e32 v12, 0x4b800000, v112
	v_cmp_gt_f32_e32 vcc, 0x800000, v112
	s_nop 1
	v_cndmask_b32_e32 v112, v112, v12, vcc
	v_rsq_f32_e32 v112, v112
	s_nop 0
	v_mul_f32_e32 v12, 0x45800000, v112
	v_cndmask_b32_e32 v112, v112, v12, vcc
	v_mul_f32_e32 v12, 0x4b800000, v113
	v_cmp_gt_f32_e32 vcc, 0x800000, v113
	s_nop 1
	v_cndmask_b32_e32 v113, v113, v12, vcc
	v_rsq_f32_e32 v113, v113
	s_nop 0
	v_mul_f32_e32 v12, 0x45800000, v113
	v_cndmask_b32_e32 v113, v113, v12, vcc
	v_mul_f32_e32 v12, 0x4b800000, v114
	v_cmp_gt_f32_e32 vcc, 0x800000, v114
	s_nop 1
	v_cndmask_b32_e32 v114, v114, v12, vcc
	v_rsq_f32_e32 v114, v114
	s_nop 0
	v_mul_f32_e32 v12, 0x45800000, v114
	v_cndmask_b32_e32 v114, v114, v12, vcc
	v_mul_f32_e32 v12, 0x4b800000, v115
	v_cmp_gt_f32_e32 vcc, 0x800000, v115
	s_nop 1
	v_cndmask_b32_e32 v115, v115, v12, vcc
	v_rsq_f32_e32 v115, v115
	s_nop 0
	v_mul_f32_e32 v12, 0x45800000, v115
	v_cndmask_b32_e32 v115, v115, v12, vcc
	s_mov_b64 s[0:1], exec
	s_mov_b64 exec, 1
	s_mov_b32 s100, s6
	s_cmp_lt_u32 s100, 0x4000
	s_cbranch_scc0 .Lssq_skip0
	s_lshl_b32 s101, s100, 2
	v_mov_b32_e32 v12, s101
	v_add_u32_e32 v12, 0xf8000, v12
	global_store_dword v12, v112, s[4:5]
.Lssq_skip0:
	s_add_u32 s100, s100, s7
	s_cmp_lt_u32 s100, 0x4000
	s_cbranch_scc0 .Lssq_skip1
	s_lshl_b32 s101, s100, 2
	v_mov_b32_e32 v12, s101
	v_add_u32_e32 v12, 0xf8000, v12
	global_store_dword v12, v113, s[4:5]
.Lssq_skip1:
	s_add_u32 s100, s100, s7
	s_cmp_lt_u32 s100, 0x4000
	s_cbranch_scc0 .Lssq_skip2
	s_lshl_b32 s101, s100, 2
	v_mov_b32_e32 v12, s101
	v_add_u32_e32 v12, 0xf8000, v12
	global_store_dword v12, v114, s[4:5]
.Lssq_skip2:
	s_add_u32 s100, s100, s7
	s_cmp_lt_u32 s100, 0x4000
	s_cbranch_scc0 .Lssq_skip3
	s_lshl_b32 s101, s100, 2
	v_mov_b32_e32 v12, s101
	v_add_u32_e32 v12, 0xf8000, v12
	global_store_dword v12, v115, s[4:5]
.Lssq_skip3:
	s_add_u32 s100, s100, s7
	s_mov_b64 exec, s[0:1]
	s_lshl_b32 s0, s7, 2
	s_add_u32 s6, s6, s0
	s_cmp_lt_u32 s6, 0x4000
	s_cbranch_scc1 .Lssq_loop
